# MLA V^T LDS image: row stride 272 B, 4-key chunks stored 0,2,1,3 so each P*V A fragment is one ds_read_b128 instead of ds_read2_b64
# speedup vs baseline: 1.0059x; 1.0059x over previous
.LBB0_811:
	s_or_b64 exec, exec, s[0:1]
	v_mov_b32_e32 v188, v0
	s_waitcnt lgkmcnt(0)
	s_barrier
	s_cmpk_gt_i32 s2, 0x3ff
	v_readfirstlane_b32 s40, v188
	s_cbranch_scc1 .LBB0_828
	v_ashrrev_i32_e32 v2, 1, v188
	s_movk_i32 s0, 0xffe0
	v_bfe_u32 v4, v188, 5, 1
	v_bfi_b32 v130, s0, v2, v188
	s_movk_i32 s10, 0x600
	v_mov_b64_e32 v[2:3], s[28:29]
	v_mov_b32_e32 v135, 0
	v_mad_i64_i32 v[2:3], s[0:1], v130, s10, v[2:3]
	v_lshlrev_b32_e32 v132, 4, v4
	v_mov_b32_e32 v133, v135
	v_lshl_add_u64 v[136:137], v[2:3], 0, v[132:133]
	v_mbcnt_hi_u32_b32 v2, -1, v254
	v_and_b32_e32 v5, 64, v2
	v_xor_b32_e32 v3, 32, v2
	v_add_u32_e32 v5, 64, v5
	v_cmp_lt_i32_e32 vcc, v3, v5
	s_mov_b32 s0, 0x2aaaaaab
	v_add_u32_e32 v6, 0x200, v188
	v_cndmask_b32_e32 v2, v2, v3, vcc
	v_lshlrev_b32_e32 v190, 2, v2
	v_mul_hi_i32 v2, v188, s0
	v_lshrrev_b32_e32 v3, 31, v2
	v_ashrrev_i32_e32 v2, 1, v2
	v_add_u32_e32 v3, v2, v3
	v_mul_lo_u32 v2, v3, 12
	v_sub_u32_e32 v5, v188, v2
	v_mul_hi_i32 v2, v6, s0
	v_lshrrev_b32_e32 v7, 31, v2
	v_ashrrev_i32_e32 v2, 1, v2
	v_add_u32_e32 v8, v2, v7
	v_mul_lo_u32 v2, v8, 12
	v_sub_u32_e32 v7, v6, v2
	v_add_u32_e32 v2, 0x400, v188
	v_mul_hi_i32 v9, v2, s0
	v_lshrrev_b32_e32 v10, 31, v9
	v_ashrrev_i32_e32 v9, 1, v9
	v_add_u32_e32 v9, v9, v10
	v_mul_lo_u32 v10, v9, 12
	v_sub_u32_e32 v10, v2, v10
	v_lshlrev_b32_e32 v152, 3, v10
	v_ashrrev_i32_e32 v153, 31, v152
	v_lshlrev_b32_e32 v148, 3, v7
	v_ashrrev_i32_e32 v156, 4, v6
	v_lshlrev_b32_e32 v195, 4, v7
	v_lshlrev_b64 v[6:7], 1, v[152:153]
	v_mad_i64_i32 v[142:143], s[6:7], v3, s10, 0
	v_mad_i64_i32 v[146:147], s[6:7], v8, s10, 0
	v_mad_i64_i32 v[150:151], s[6:7], v9, s10, 0
	v_mad_i64_i32 v[6:7], s[6:7], v9, s10, v[6:7]
	v_ashrrev_i32_e32 v149, 31, v148
	s_mov_b64 s[6:7], 0xa400000
	v_lshlrev_b32_e32 v144, 3, v5
	v_lshl_add_u64 v[166:167], v[6:7], 0, s[6:7]
	v_lshlrev_b64 v[6:7], 1, v[148:149]
	v_readlane_b32 s48, v255, 2
	v_ashrrev_i32_e32 v145, 31, v144
	v_mad_i64_i32 v[6:7], s[8:9], v8, s10, v[6:7]
	v_and_b32_e32 v1, 31, v188
	v_lshlrev_b32_e32 v134, 5, v4
	v_readlane_b32 s60, v255, 14
	v_readlane_b32 s61, v255, 15
	v_lshlrev_b32_e32 v2, 3, v188
	v_ashrrev_i32_e32 v154, 4, v188
	s_movk_i32 s0, 0xd0
	v_lshlrev_b32_e32 v192, 4, v5
	v_lshlrev_b32_e32 v5, 4, v188
	v_lshl_add_u64 v[168:169], v[6:7], 0, s[6:7]
	v_lshlrev_b64 v[6:7], 1, v[144:145]
	v_ashrrev_i32_e32 v131, 31, v130
	v_lshlrev_b32_e32 v189, 4, v4
	v_lshl_add_u64 v[138:139], s[60:61], 0, v[134:135]
	v_lshlrev_b32_e32 v134, 6, v4
	v_and_b32_e32 v2, 0x78, v2
	v_ashrrev_i32_e32 v155, 31, v154
	v_ashrrev_i32_e32 v157, 31, v156
	v_mul_lo_u32 v191, v3, s0
	v_mul_lo_u32 v194, v8, s0
	v_mul_lo_u32 v197, v9, s0
	v_lshlrev_b32_e32 v198, 4, v10
	v_and_b32_e32 v200, 0xe0, v5
	v_and_b32_e32 v201, 1, v188
	v_lshl_or_b32 v200, v201, 3, v200
	s_movk_i32 s0, 0x110
	v_mul_u32_u24_e32 v204, 0xd0, v1
	v_mul_u32_u24_e32 v205, 0x110, v1
	v_lshlrev_b32_e32 v4, 2, v4
	v_and_b32_e32 v1, 15, v188
	v_mad_i64_i32 v[6:7], s[8:9], v3, s10, v[6:7]
	s_mov_b32 s1, 0
	v_lshl_add_u64 v[140:141], s[44:45], 0, v[134:135]
	v_add3_u32 v193, 0, v191, v192
	v_add3_u32 v196, 0, v194, v195
	v_add3_u32 v199, 0, v197, v198
	v_add_u32_e32 v201, 0, v200
	v_mul_lo_u32 v202, v154, s0
	v_mul_lo_u32 v203, v156, s0
	v_lshlrev_b64 v[158:159], 10, v[130:131]
	v_lshlrev_b32_e32 v160, 4, v1
	v_mov_b32_e32 v161, v135
	v_lshlrev_b64 v[162:163], 1, v[154:155]
	v_lshlrev_b64 v[164:165], 1, v[156:157]
	v_lshl_add_u64 v[170:171], v[6:7], 0, s[6:7]
	v_mov_b32_e32 v157, 0x358637bd
	s_mov_b32 s41, 0x800000
	s_movk_i32 s44, 0x6800
	s_mov_b32 s45, 0xff800000
	s_add_u32 s98, s78, 0xd3d0000
	s_addc_u32 s99, s79, 0
	s_mov_b64 s[6:7], 0x100
	s_mov_b64 s[8:9], 0x30000
	v_lshlrev_b32_e32 v134, 1, v4
	v_mov_b32_e32 v206, 0xc0
	v_lshlrev_b32_e32 v172, 1, v2
	v_mov_b32_e32 v207, 0x600
	s_mov_b32 s48, s2
	v_readlane_b32 s49, v255, 3
	v_readlane_b32 s50, v255, 4
	v_readlane_b32 s51, v255, 5
	v_readlane_b32 s52, v255, 6
	v_readlane_b32 s53, v255, 7
	v_readlane_b32 s54, v255, 8
	v_readlane_b32 s55, v255, 9
	v_readlane_b32 s56, v255, 10
	v_readlane_b32 s57, v255, 11
	v_readlane_b32 s58, v255, 12
	v_readlane_b32 s59, v255, 13
	v_readlane_b32 s62, v255, 16
	v_readlane_b32 s63, v255, 17
	v_mbcnt_lo_u32_b32 v236, -1, 0
	v_mbcnt_hi_u32_b32 v236, -1, v236
	v_lshlrev_b32_e32 v236, 2, v236
	global_load_dword v237, v236, s[60:61]
	global_load_dword v238, v236, s[60:61] offset:128
	global_load_dword v240, v236, s[62:63]
	global_load_dword v241, v236, s[62:63] offset:128
	s_waitcnt vmcnt(0)
	v_max_f32_e64 v237, |v237|, |v238|
	v_max_f32_e64 v240, |v240|, |v241|
	v_xor_b32_e32 v238, 4, v236
	ds_bpermute_b32 v241, v238, v237
	ds_bpermute_b32 v242, v238, v240
	s_waitcnt lgkmcnt(0)
	v_max_f32_e32 v237, v237, v241
	v_max_f32_e32 v240, v240, v242
	v_xor_b32_e32 v238, 8, v236
	ds_bpermute_b32 v241, v238, v237
	ds_bpermute_b32 v242, v238, v240
	s_waitcnt lgkmcnt(0)
	v_max_f32_e32 v237, v237, v241
	v_max_f32_e32 v240, v240, v242
	v_xor_b32_e32 v238, 16, v236
	ds_bpermute_b32 v241, v238, v237
	ds_bpermute_b32 v242, v238, v240
	s_waitcnt lgkmcnt(0)
	v_max_f32_e32 v237, v237, v241
	v_max_f32_e32 v240, v240, v242
	v_xor_b32_e32 v238, 32, v236
	ds_bpermute_b32 v241, v238, v237
	ds_bpermute_b32 v242, v238, v240
	s_waitcnt lgkmcnt(0)
	v_max_f32_e32 v237, v237, v241
	v_max_f32_e32 v240, v240, v242
	v_xor_b32_e32 v238, 64, v236
	ds_bpermute_b32 v241, v238, v237
	ds_bpermute_b32 v242, v238, v240
	s_waitcnt lgkmcnt(0)
	v_max_f32_e32 v237, v237, v241
	v_max_f32_e32 v240, v240, v242
	v_xor_b32_e32 v238, 128, v236
	ds_bpermute_b32 v241, v238, v237
	ds_bpermute_b32 v242, v238, v240
	s_waitcnt lgkmcnt(0)
	v_max_f32_e32 v237, v237, v241
	v_max_f32_e32 v240, v240, v242
	v_mul_f32_e32 v237, v237, v240
	s_mov_b32 s100, 0
	v_cmp_gt_f32_e32 vcc, 4.0, v237
	s_nop 3
	s_cmp_lg_u64 vcc, 0
	s_cselect_b32 s100, 1, 0
	s_branch .LBB0_814
.LBB0_813:
	s_barrier
	s_setprio 1
	v_sub_f32_e32 v66, v66, v98
	v_exp_f32_e32 v99, v66
	v_sub_f32_e32 v66, v67, v98
	v_exp_f32_e32 v100, v66
	v_sub_f32_e32 v66, v68, v98
	v_exp_f32_e32 v101, v66
	v_sub_f32_e32 v66, v69, v98
	v_exp_f32_e32 v102, v66
	v_sub_f32_e32 v66, v70, v98
	v_exp_f32_e32 v103, v66
	v_sub_f32_e32 v66, v71, v98
	v_exp_f32_e32 v104, v66
	v_sub_f32_e32 v66, v72, v98
	v_exp_f32_e32 v105, v66
	v_sub_f32_e32 v66, v73, v98
	v_exp_f32_e32 v106, v66
	v_sub_f32_e32 v66, v74, v98
	v_exp_f32_e32 v74, v66
	v_sub_f32_e32 v66, v75, v98
	v_exp_f32_e32 v75, v66
	v_sub_f32_e32 v66, v76, v98
	v_exp_f32_e32 v76, v66
	v_sub_f32_e32 v66, v77, v98
	v_exp_f32_e32 v77, v66
	v_sub_f32_e32 v66, v78, v98
	v_exp_f32_e32 v78, v66
	v_sub_f32_e32 v66, v79, v98
	v_exp_f32_e32 v79, v66
	v_sub_f32_e32 v66, v80, v98
	v_add3_u32 v70, s0, v189, v205
	v_exp_f32_e32 v80, v66
	v_sub_f32_e32 v66, v81, v98
	v_add_u32_e32 v109, 0x6800, v70
	v_exp_f32_e32 v81, v66
	ds_read_b128 v[66:69], v109
	v_sub_f32_e32 v82, v82, v98
	v_sub_f32_e32 v83, v83, v98
	v_sub_f32_e32 v84, v84, v98
	v_sub_f32_e32 v85, v85, v98
	v_sub_f32_e32 v86, v86, v98
	v_sub_f32_e32 v87, v87, v98
	v_sub_f32_e32 v88, v88, v98
	v_sub_f32_e32 v89, v89, v98
	v_add_u32_e32 v112, 0x8900, v70
	v_exp_f32_e32 v82, v82
	v_exp_f32_e32 v83, v83
	v_exp_f32_e32 v84, v84
	v_exp_f32_e32 v85, v85
	v_exp_f32_e32 v86, v86
	v_exp_f32_e32 v87, v87
	v_exp_f32_e32 v88, v88
	v_exp_f32_e32 v89, v89
	ds_read_b128 v[70:73], v112 offset:256
	v_sub_f32_e32 v50, v50, v98
	v_exp_f32_e32 v107, v50
	v_sub_f32_e32 v50, v51, v98
	v_exp_f32_e32 v108, v50
	v_sub_f32_e32 v50, v52, v98
	v_exp_f32_e32 v110, v50
	v_sub_f32_e32 v111, v53, v98
	v_cvt_pk_bf16_f32 v50, v82, v83
	v_cvt_pk_bf16_f32 v51, v84, v85
	v_cvt_pk_bf16_f32 v52, v86, v87
	v_cvt_pk_bf16_f32 v53, v88, v89
	v_sub_f32_e32 v54, v54, v98
	v_exp_f32_e32 v113, v54
	s_waitcnt lgkmcnt(1)
	v_mfma_f32_32x32x16_bf16 v[18:33], v[66:69], v[50:53], v[18:33]
	ds_read_b128 v[66:69], v109 offset:32
	v_sub_f32_e32 v54, v55, v98
	v_sub_f32_e32 v90, v90, v98
	v_sub_f32_e32 v91, v91, v98
	v_sub_f32_e32 v92, v92, v98
	v_sub_f32_e32 v93, v93, v98
	v_sub_f32_e32 v94, v94, v98
	v_sub_f32_e32 v95, v95, v98
	v_sub_f32_e32 v96, v96, v98
	v_sub_f32_e32 v97, v97, v98
	v_exp_f32_e32 v114, v54
	v_sub_f32_e32 v54, v56, v98
	v_exp_f32_e32 v90, v90
	v_exp_f32_e32 v91, v91
	v_exp_f32_e32 v92, v92
	v_exp_f32_e32 v93, v93
	v_exp_f32_e32 v94, v94
	v_exp_f32_e32 v95, v95
	v_exp_f32_e32 v96, v96
	v_exp_f32_e32 v97, v97
	s_waitcnt lgkmcnt(1)
	v_mfma_f32_32x32x16_bf16 v[2:17], v[70:73], v[50:53], v[2:17]
	v_exp_f32_e32 v70, v54
	v_sub_f32_e32 v71, v57, v98
	ds_read_b128 v[54:57], v112 offset:288
	v_cvt_pk_bf16_f32 v50, v90, v91
	v_cvt_pk_bf16_f32 v51, v92, v93
	v_cvt_pk_bf16_f32 v52, v94, v95
	v_cvt_pk_bf16_f32 v53, v96, v97
	v_sub_f32_e32 v58, v58, v98
	v_exp_f32_e32 v72, v58
	s_waitcnt lgkmcnt(1)
	v_mfma_f32_32x32x16_bf16 v[18:33], v[66:69], v[50:53], v[18:33]
	ds_read_b128 v[66:69], v109 offset:64
	v_sub_f32_e32 v58, v59, v98
	v_exp_f32_e32 v73, v58
	v_sub_f32_e32 v58, v60, v98
	v_exp_f32_e32 v115, v58
	v_sub_f32_e32 v58, v61, v98
	v_exp_f32_e32 v111, v111
	s_waitcnt lgkmcnt(1)
	v_mfma_f32_32x32x16_bf16 v[2:17], v[54:57], v[50:53], v[2:17]
	ds_read_b128 v[54:57], v112 offset:320
	v_cvt_pk_bf16_f32 v50, v99, v100
	v_cvt_pk_bf16_f32 v51, v101, v102
	v_cvt_pk_bf16_f32 v52, v103, v104
	v_cvt_pk_bf16_f32 v53, v105, v106
	v_exp_f32_e32 v71, v71
	v_sub_f32_e32 v34, v34, v98
	s_waitcnt lgkmcnt(1)
	v_mfma_f32_32x32x16_bf16 v[18:33], v[66:69], v[50:53], v[18:33]
	v_exp_f32_e32 v66, v58
	v_sub_f32_e32 v58, v62, v98
	v_exp_f32_e32 v62, v58
	v_sub_f32_e32 v58, v63, v98
	v_exp_f32_e32 v63, v58
	ds_read_b128 v[58:61], v109 offset:96
	v_exp_f32_e32 v67, v34
	s_waitcnt lgkmcnt(1)
	v_mfma_f32_32x32x16_bf16 v[2:17], v[54:57], v[50:53], v[2:17]
	ds_read_b128 v[54:57], v112 offset:352
	v_cvt_pk_bf16_f32 v50, v74, v75
	v_cvt_pk_bf16_f32 v51, v76, v77
	v_cvt_pk_bf16_f32 v52, v78, v79
	v_cvt_pk_bf16_f32 v53, v80, v81
	v_sub_f32_e32 v34, v35, v98
	v_exp_f32_e32 v68, v34
	s_waitcnt lgkmcnt(1)
	v_mfma_f32_32x32x16_bf16 v[18:33], v[58:61], v[50:53], v[18:33]
	ds_read_b128 v[58:61], v109 offset:128
	v_sub_f32_e32 v34, v36, v98
	v_exp_f32_e32 v69, v34
	v_cvt_pk_bf16_f32 v34, v107, v108
	v_cvt_pk_bf16_f32 v35, v110, v111
	v_cvt_pk_bf16_f32 v36, v113, v114
	v_sub_f32_e32 v38, v38, v98
	s_waitcnt lgkmcnt(1)
	v_mfma_f32_32x32x16_bf16 v[2:17], v[54:57], v[50:53], v[2:17]
	ds_read_b128 v[50:53], v112 offset:384
	v_sub_f32_e32 v54, v37, v98
	v_cvt_pk_bf16_f32 v37, v70, v71
	v_sub_f32_e32 v64, v64, v98
	v_sub_f32_e32 v65, v65, v98
	v_exp_f32_e32 v64, v64
	v_exp_f32_e32 v65, v65
	s_waitcnt lgkmcnt(1)
	v_mfma_f32_32x32x16_bf16 v[18:33], v[58:61], v[34:37], v[18:33]
	v_exp_f32_e32 v58, v54
	v_exp_f32_e32 v59, v38
	v_sub_f32_e32 v38, v39, v98
	ds_read_b128 v[54:57], v109 offset:160
	v_exp_f32_e32 v60, v38
	v_sub_f32_e32 v38, v40, v98
	v_exp_f32_e32 v61, v38
	s_waitcnt lgkmcnt(1)
	v_mfma_f32_32x32x16_bf16 v[2:17], v[50:53], v[34:37], v[2:17]
	v_sub_f32_e32 v50, v41, v98
	ds_read_b128 v[38:41], v112 offset:416
	v_cvt_pk_bf16_f32 v34, v72, v73
	v_cvt_pk_bf16_f32 v35, v115, v66
	v_cvt_pk_bf16_f32 v36, v62, v63
	v_cvt_pk_bf16_f32 v37, v64, v65
	v_sub_f32_e32 v42, v42, v98
	v_sub_f32_e32 v48, v48, v98
	s_waitcnt lgkmcnt(1)
	v_mfma_f32_32x32x16_bf16 v[18:33], v[54:57], v[34:37], v[18:33]
	v_exp_f32_e32 v54, v50
	ds_read_b128 v[50:53], v109 offset:192
	v_exp_f32_e32 v55, v42
	v_sub_f32_e32 v42, v43, v98
	v_exp_f32_e32 v56, v42
	v_sub_f32_e32 v42, v44, v98
	v_exp_f32_e32 v57, v42
	s_waitcnt lgkmcnt(1)
	v_mfma_f32_32x32x16_bf16 v[2:17], v[38:41], v[34:37], v[2:17]
	ds_read_b128 v[38:41], v112 offset:448
	v_sub_f32_e32 v42, v45, v98
	v_cvt_pk_bf16_f32 v34, v67, v68
	v_cvt_pk_bf16_f32 v35, v69, v58
	v_cvt_pk_bf16_f32 v36, v59, v60
	v_cvt_pk_bf16_f32 v37, v61, v54
	v_exp_f32_e32 v48, v48
	s_lshl_b64 s[10:11], s[10:11], 10
	s_waitcnt lgkmcnt(1)
	v_mfma_f32_32x32x16_bf16 v[18:33], v[50:53], v[34:37], v[18:33]
	v_exp_f32_e32 v50, v42
	v_sub_f32_e32 v42, v46, v98
	v_exp_f32_e32 v46, v42
	v_sub_f32_e32 v42, v47, v98
	v_exp_f32_e32 v47, v42
	ds_read_b128 v[42:45], v109 offset:224
	s_add_u32 s0, s36, s10
	s_waitcnt lgkmcnt(1)
	v_mfma_f32_32x32x16_bf16 v[2:17], v[38:41], v[34:37], v[2:17]
	ds_read_b128 v[38:41], v112 offset:480
	v_sub_f32_e32 v34, v49, v98
	v_exp_f32_e32 v49, v34
	v_cvt_pk_bf16_f32 v34, v55, v56
	v_cvt_pk_bf16_f32 v35, v57, v50
	v_cvt_pk_bf16_f32 v36, v46, v47
	v_cvt_pk_bf16_f32 v37, v48, v49
	s_addc_u32 s11, s37, s11
	s_lshl_b32 s10, s49, 7
	s_waitcnt lgkmcnt(1)
	v_mfma_f32_32x32x16_bf16 v[18:33], v[42:45], v[34:37], v[18:33]
	s_add_u32 s10, s0, s10
	s_addc_u32 s11, s11, 0
	s_waitcnt lgkmcnt(0)
	s_cmpk_lt_i32 s40, 0x100
	s_cbranch_scc0 .Lmla_fin_nobar
	s_barrier

.LBB0_821:
	v_mov_b32_e32 v101, v1
	s_waitcnt lgkmcnt(0)
	v_add_f32_e32 v1, v102, v105
	v_fmamk_f32 v1, v1, 0x3c2aaaab, v157
	v_mul_f32_e32 v102, 0x4b800000, v1
	v_cmp_gt_f32_e32 vcc, s41, v1
	v_mov_b32_e32 v123, v133
	v_mov_b32_e32 v109, v103
	v_cndmask_b32_e32 v1, v1, v102, vcc
	v_rsq_f32_e32 v1, v1
	v_mov_b32_e32 v121, v131
	v_mov_b32_e32 v105, v127
	v_mov_b32_e32 v119, v155
	v_mul_f32_e32 v102, 0x45800000, v1
	v_cndmask_b32_e32 v1, v1, v102, vcc
	v_mul_f32_e32 v124, 0x3e16c740, v1
	v_pk_mul_f32 v[102:103], v[124:125], v[122:123] op_sel_hi:[0,1]
	s_waitcnt vmcnt(4)
	v_pk_mul_f32 v[62:63], v[62:63], v[102:103]
	v_mov_b32_e32 v99, v111
	v_cvt_pk_bf16_f32 v102, v62, v63
	v_pk_mul_f32 v[62:63], v[124:125], v[120:121] op_sel_hi:[0,1]
	v_pk_mul_f32 v[62:63], v[64:65], v[62:63]
	v_mov_b32_e32 v111, v181
	v_cvt_pk_bf16_f32 v103, v62, v63
	v_pk_mul_f32 v[62:63], v[124:125], v[104:105] op_sel_hi:[0,1]
	v_pk_mul_f32 v[58:59], v[58:59], v[62:63]
	v_mov_b32_e32 v95, v117
	v_cvt_pk_bf16_f32 v104, v58, v59
	v_pk_mul_f32 v[58:59], v[124:125], v[118:119] op_sel_hi:[0,1]
	v_pk_mul_f32 v[58:59], v[60:61], v[58:59]
	v_mov_b32_e32 v117, v183
	v_cvt_pk_bf16_f32 v105, v58, v59
	v_pk_mul_f32 v[58:59], v[124:125], v[110:111] op_sel_hi:[0,1]
	v_pk_mul_f32 v[54:55], v[54:55], v[58:59]
	v_mov_b32_e32 v107, v113
	v_cvt_pk_bf16_f32 v110, v54, v55
	v_pk_mul_f32 v[54:55], v[124:125], v[116:117] op_sel_hi:[0,1]
	v_mov_b32_e32 v113, v185
	v_pk_mul_f32 v[54:55], v[56:57], v[54:55]
	v_mov_b32_e32 v97, v115
	v_cvt_pk_bf16_f32 v111, v54, v55
	v_pk_mul_f32 v[54:55], v[124:125], v[112:113] op_sel_hi:[0,1]
	v_mov_b32_e32 v115, v187
	v_pk_mul_f32 v[50:51], v[50:51], v[54:55]
	s_lshl_b64 s[38:39], s[12:13], 3
	v_cvt_pk_bf16_f32 v112, v50, v51
	v_pk_mul_f32 v[50:51], v[124:125], v[114:115] op_sel_hi:[0,1]
	v_pk_mul_f32 v[50:51], v[52:53], v[50:51]
	s_or_b32 s0, s38, s49
	v_cvt_pk_bf16_f32 v113, v50, v51
	v_pk_mul_f32 v[50:51], v[124:125], v[98:99] op_sel_hi:[0,1]
	v_pk_mul_f32 v[46:47], v[46:47], v[50:51]
	s_mul_i32 s13, s39, 0xc0
	v_cvt_pk_bf16_f32 v98, v46, v47
	v_pk_mul_f32 v[46:47], v[124:125], v[108:109] op_sel_hi:[0,1]
	v_pk_mul_f32 v[46:47], v[46:47], v[48:49]
	s_mul_hi_u32 s15, s0, 0xc0
	v_cvt_pk_bf16_f32 v99, v46, v47
	v_pk_mul_f32 v[46:47], v[124:125], v[100:101] op_sel_hi:[0,1]
	v_pk_mul_f32 v[42:43], v[46:47], v[42:43]
	v_mov_b32_e32 v93, v125
	v_cvt_pk_bf16_f32 v100, v42, v43
	v_pk_mul_f32 v[42:43], v[124:125], v[106:107] op_sel_hi:[0,1]
	v_pk_mul_f32 v[42:43], v[42:43], v[44:45]
	s_add_i32 s15, s15, s13
	v_cvt_pk_bf16_f32 v101, v42, v43
	v_pk_mul_f32 v[42:43], v[124:125], v[96:97] op_sel_hi:[0,1]
	v_pk_mul_f32 v[38:39], v[42:43], v[38:39]
	s_mulk_i32 s0, 0xc0
	v_cvt_pk_bf16_f32 v106, v38, v39
	v_pk_mul_f32 v[38:39], v[124:125], v[94:95] op_sel_hi:[0,1]
	v_pk_mul_f32 v[38:39], v[38:39], v[40:41]
	s_add_u32 s38, s42, s0
	v_cvt_pk_bf16_f32 v107, v38, v39
	v_pk_mul_f32 v[38:39], v[124:125], v[92:93] op_sel_hi:[0,1]
	v_mov_b32_e32 v91, v179
	v_pk_mul_f32 v[34:35], v[38:39], v[34:35]
	s_addc_u32 s39, s43, s15
	s_lshl_b32 s0, s34, 1
	v_cvt_pk_bf16_f32 v108, v34, v35
	v_pk_mul_f32 v[34:35], v[124:125], v[90:91] op_sel_hi:[0,1]
	s_add_u32 s51, s46, s0
	s_mul_hi_i32 s35, s50, s14
	s_mul_i32 s34, s50, s14
	v_pk_mul_f32 v[34:35], v[34:35], v[36:37]
	s_addc_u32 s52, s47, 0
	s_ashr_i32 s15, s14, 31
	s_lshl_b64 s[34:35], s[34:35], 7
	v_cvt_pk_bf16_f32 v109, v34, v35
	v_pk_mul_f32 v[34:35], v[124:125], v[86:87] op_sel_hi:[0,1]
	v_mov_b32_e32 v36, v10
	v_mov_b32_e32 v37, v15
	s_add_u32 s34, s51, s34
	v_pk_mul_f32 v[54:55], v[34:35], v[36:37]
	v_lshl_add_u64 v[36:37], s[38:39], 0, v[146:147]
	s_addc_u32 s35, s52, s35
	v_pk_mul_f32 v[34:35], v[124:125], v[84:85] op_sel_hi:[0,1]
	v_mov_b32_e32 v15, v11
	v_lshl_add_u64 v[38:39], v[148:149], 1, v[36:37]
	v_lshl_add_u64 v[36:37], s[38:39], 0, v[150:151]
	v_mov_b32_e32 v173, v135
	v_pk_mul_f32 v[10:11], v[34:35], v[14:15]
	v_lshl_add_u64 v[34:35], s[38:39], 0, v[142:143]
	v_lshl_add_u64 v[46:47], v[152:153], 1, v[36:37]
	v_lshl_add_u64 v[50:51], s[34:35], 0, v[172:173]
	v_mad_i64_i32 v[36:37], s[34:35], s50, v154, 0
	v_lshl_add_u64 v[34:35], v[144:145], 1, v[34:35]
	v_lshl_add_u64 v[42:43], v[36:37], 1, v[50:51]
	v_mad_i64_i32 v[52:53], s[34:35], s50, v156, 0
	global_load_dwordx4 v[34:37], v[34:35], off
	s_nop 0
	global_load_dwordx4 v[38:41], v[38:39], off
	s_nop 0
	global_load_dwordx4 v[42:45], v[42:43], off
	s_nop 0
	global_load_dwordx4 v[46:49], v[46:47], off
	v_lshl_add_u64 v[50:51], v[52:53], 1, v[50:51]
	global_load_dwordx4 v[50:53], v[50:51], off
	s_waitcnt vmcnt(5)
	v_mov_b32_e32 v88, v31
	v_mov_b32_e32 v89, v32
	v_mov_b32_e32 v77, v129
	v_mov_b32_e32 v57, v32
	v_mov_b32_e32 v58, v10
	v_mov_b32_e32 v59, v55
	v_mov_b32_e32 v32, v31
	v_mov_b32_e32 v31, v33
	v_mov_b32_e32 v15, v11
	v_mov_b32_e32 v56, v30
	v_pk_mul_f32 v[58:59], v[58:59], v[32:33]
	v_pk_mul_f32 v[10:11], v[10:11], v[30:31]
	v_pk_mul_f32 v[30:31], v[124:125], v[76:77] op_sel_hi:[0,1]
	v_mov_b32_e32 v32, v12
	v_mov_b32_e32 v33, v17
	v_pk_mul_f32 v[30:31], v[30:31], v[32:33]
	v_pk_mul_f32 v[32:33], v[124:125], v[74:75] op_sel_hi:[0,1]
	v_mov_b32_e32 v17, v13
	v_pk_mul_f32 v[12:13], v[32:33], v[16:17]
	v_mov_b32_e32 v82, v27
	v_mov_b32_e32 v83, v28
	v_mov_b32_e32 v73, v175
	v_mov_b32_e32 v14, v54
	v_pk_fma_f32 v[10:11], v[54:55], v[88:89], v[10:11]
	v_mov_b32_e32 v33, v28
	v_mov_b32_e32 v54, v12
	v_mov_b32_e32 v55, v31
	v_mov_b32_e32 v28, v27
	v_mov_b32_e32 v27, v29
	v_mov_b32_e32 v17, v13
	v_mov_b32_e32 v32, v26
	v_pk_mul_f32 v[54:55], v[54:55], v[28:29]
	v_pk_mul_f32 v[12:13], v[12:13], v[26:27]
	v_pk_mul_f32 v[26:27], v[124:125], v[72:73] op_sel_hi:[0,1]
	v_mov_b32_e32 v28, v2
	v_mov_b32_e32 v29, v7
	v_pk_mul_f32 v[26:27], v[26:27], v[28:29]
	v_pk_mul_f32 v[28:29], v[124:125], v[70:71] op_sel_hi:[0,1]
	v_mov_b32_e32 v7, v3
	v_pk_mul_f32 v[2:3], v[28:29], v[6:7]
	v_mov_b32_e32 v80, v23
	v_mov_b32_e32 v81, v24
	v_mov_b32_e32 v69, v177
	v_mov_b32_e32 v16, v30
	v_pk_fma_f32 v[12:13], v[30:31], v[82:83], v[12:13]
	v_mov_b32_e32 v29, v24
	v_mov_b32_e32 v30, v2
	v_mov_b32_e32 v31, v27
	v_mov_b32_e32 v24, v23
	v_mov_b32_e32 v23, v25
	v_mov_b32_e32 v7, v3
	v_mov_b32_e32 v28, v22
	v_pk_mul_f32 v[30:31], v[30:31], v[24:25]
	v_pk_mul_f32 v[2:3], v[2:3], v[22:23]
	v_pk_mul_f32 v[22:23], v[124:125], v[68:69] op_sel_hi:[0,1]
	v_mov_b32_e32 v24, v4
	v_mov_b32_e32 v25, v9
	v_pk_mul_f32 v[22:23], v[22:23], v[24:25]
	v_pk_mul_f32 v[24:25], v[124:125], v[66:67] op_sel_hi:[0,1]
	v_mov_b32_e32 v9, v5
	v_mov_b32_e32 v78, v19
	v_mov_b32_e32 v79, v20
	v_pk_mul_f32 v[4:5], v[24:25], v[8:9]
	v_mov_b32_e32 v25, v20
	v_mov_b32_e32 v20, v19
	v_mov_b32_e32 v19, v21
	v_mov_b32_e32 v6, v26
	v_pk_fma_f32 v[2:3], v[26:27], v[80:81], v[2:3]
	v_mov_b32_e32 v9, v5
	v_mov_b32_e32 v26, v4
	v_pk_mul_f32 v[4:5], v[4:5], v[18:19]
	s_lshl_b64 s[14:15], s[14:15], 7
	v_pk_fma_f32 v[4:5], v[22:23], v[78:79], v[4:5]
	v_cvt_pk_bf16_f32 v116, v2, v3
	v_lshl_add_u64 v[2:3], v[162:163], 0, s[14:15]
	v_cvt_pk_bf16_f32 v117, v4, v5
	v_mad_u64_u32 v[4:5], s[38:39], v2, s50, v[160:161]
	v_mad_i32_i24 v5, v3, s50, v5
	v_lshl_add_u64 v[2:3], v[164:165], 0, s[14:15]
	v_lshl_add_u64 v[174:175], v[4:5], 0, s[0:1]
	v_mad_u64_u32 v[4:5], s[14:15], v2, s50, v[160:161]
	v_mov_b32_e32 v27, v23
	v_mad_i32_i24 v5, v3, s50, v5
	v_mad_i64_i32 v[2:3], s[14:15], s12, v207, v[166:167]
	v_pk_fma_f32 v[16:17], v[16:17], v[32:33], v[54:55] neg_lo:[0,0,1] neg_hi:[0,0,1]
	v_mov_b32_e32 v8, v22
	v_mov_b32_e32 v24, v18
	v_pk_mul_f32 v[26:27], v[26:27], v[20:21]
	v_mad_u64_u32 v[178:179], s[14:15], s49, v206, v[2:3]
	v_mad_i64_i32 v[2:3], s[14:15], s12, v207, v[168:169]
	v_pk_fma_f32 v[14:15], v[14:15], v[56:57], v[58:59] neg_lo:[0,0,1] neg_hi:[0,0,1]
	v_pk_fma_f32 v[6:7], v[6:7], v[28:29], v[30:31] neg_lo:[0,0,1] neg_hi:[0,0,1]
	v_pk_fma_f32 v[8:9], v[8:9], v[24:25], v[26:27] neg_lo:[0,0,1] neg_hi:[0,0,1]
	v_cvt_pk_bf16_f32 v119, v16, v17
	v_add3_u32 v1, v201, v202, s44
	v_mad_u64_u32 v[180:181], s[14:15], s49, v206, v[2:3]
	v_mad_i64_i32 v[2:3], s[14:15], s12, v207, v[170:171]
	v_mov_b32_e32 v16, v135
	v_mov_b32_e32 v17, v135
	v_cvt_pk_bf16_f32 v118, v14, v15
	v_cvt_pk_bf16_f32 v120, v6, v7
	v_cvt_pk_bf16_f32 v121, v8, v9
	v_cvt_pk_bf16_f32 v114, v10, v11
	v_cvt_pk_bf16_f32 v115, v12, v13
	s_waitcnt vmcnt(4)
	ds_write_b128 v193, v[34:37]
	s_waitcnt vmcnt(3)
	ds_write_b128 v196, v[38:41]
	s_waitcnt vmcnt(1)
	ds_write_b128 v199, v[46:49]
	ds_write2_b64 v1, v[42:43], v[44:45] offset1:2
	v_add3_u32 v1, v201, v203, s44
	v_lshl_add_u64 v[176:177], v[4:5], 0, s[0:1]
	v_mad_u64_u32 v[182:183], s[14:15], s49, v206, v[2:3]
	v_mov_b32_e32 v2, v135
	v_mov_b32_e32 v3, v135
	v_mov_b32_e32 v4, v135
	v_mov_b32_e32 v5, v135
	v_mov_b32_e32 v6, v135
	v_mov_b32_e32 v7, v135
	v_mov_b32_e32 v8, v135
	v_mov_b32_e32 v9, v135
	v_mov_b32_e32 v10, v135
	v_mov_b32_e32 v11, v135
	v_mov_b32_e32 v12, v135
	v_mov_b32_e32 v13, v135
	v_mov_b32_e32 v14, v135
	v_mov_b32_e32 v15, v135
	v_mov_b64_e32 v[32:33], v[16:17]
	s_mov_b32 s13, 1
	s_lshr_b32 s34, s50, 7
	s_waitcnt vmcnt(0)
	ds_write2_b64 v1, v[50:51], v[52:53] offset1:2
	v_lshl_add_u64 v[236:237], s[78:79], 0, v[182:183]
	v_lshl_add_u64 v[238:239], s[78:79], 0, v[180:181]
	v_lshl_add_u64 v[240:241], s[78:79], 0, v[178:179]
	global_load_dwordx4 v[224:227], v[236:237], off
	global_load_dwordx4 v[228:231], v[238:239], off
	global_load_dwordx4 v[232:235], v[240:241], off
	v_lshl_add_u64 v[178:179], v[178:179], 0, s[8:9]
	v_lshl_add_u64 v[180:181], v[180:181], 0, s[8:9]
	v_lshl_add_u64 v[182:183], v[182:183], 0, s[8:9]
	v_mov_b32_e32 v133, 0xff800000
	v_mov_b32_e32 v1, 0
	v_mov_b64_e32 v[30:31], v[14:15]
	v_mov_b64_e32 v[28:29], v[12:13]
	v_mov_b64_e32 v[26:27], v[10:11]
	v_mov_b64_e32 v[24:25], v[8:9]
	v_mov_b64_e32 v[22:23], v[6:7]
	v_mov_b64_e32 v[20:21], v[4:5]
	v_mov_b64_e32 v[18:19], v[2:3]
	s_waitcnt lgkmcnt(0)
	s_barrier
	s_cmpk_lt_i32 s40, 0x100
	s_cbranch_scc1 .Lmla_noskew
	s_barrier

.LBB0_822:
	s_setprio 0
	s_and_b32 s0, 1, s13
	s_cselect_b32 s12, 0, 0xac00
	s_cselect_b32 s0, 0xac00, 0
	s_add_i32 s12, s12, 0
	v_lshl_add_u64 v[248:249], s[98:99], 0, v[174:175]
	v_lshl_add_u64 v[250:251], s[98:99], 0, v[176:177]
	v_add3_u32 v236, s0, v191, v192
	v_add3_u32 v237, s0, v194, v195
	global_load_dwordx4 v[240:243], v[248:249], off offset:256
	global_load_dwordx4 v[244:247], v[250:251], off offset:256
	v_add3_u32 v238, s0, v197, v198
	v_add3_u32 v131, s12, v132, v204
	s_waitcnt vmcnt(2)
	ds_write_b128 v236, v[224:227]
	ds_write_b128 v237, v[228:231]
	ds_write_b128 v238, v[232:235]
	ds_read_b128 v[122:125], v131
	ds_read_b128 v[126:129], v131 offset:6656
	ds_read_b128 v[184:187], v131 offset:13312
	ds_read_b128 v[208:211], v131 offset:19968
	ds_read_b128 v[212:215], v131 offset:32
	ds_read_b128 v[216:219], v131 offset:6688
	s_waitcnt lgkmcnt(5)
	v_mfma_f32_32x32x16_bf16 v[82:97], v[122:125], v[102:105], 0
	ds_read_b128 v[122:125], v131 offset:13344
	s_waitcnt lgkmcnt(5)
	v_mfma_f32_32x32x16_bf16 v[66:81], v[126:129], v[102:105], 0
	ds_read_b128 v[126:129], v131 offset:20000
	s_waitcnt lgkmcnt(5)
	v_mfma_f32_32x32x16_bf16 v[50:65], v[184:187], v[102:105], 0
	ds_read_b128 v[184:187], v131 offset:64
	s_waitcnt lgkmcnt(5)
	v_mfma_f32_32x32x16_bf16 v[34:49], v[208:211], v[102:105], 0
	ds_read_b128 v[208:211], v131 offset:6720
	s_waitcnt lgkmcnt(5)
	v_mfma_f32_32x32x16_bf16 v[82:97], v[212:215], v[110:113], v[82:97]
	ds_read_b128 v[212:215], v131 offset:13376
	s_waitcnt lgkmcnt(5)
	v_mfma_f32_32x32x16_bf16 v[66:81], v[216:219], v[110:113], v[66:81]
	ds_read_b128 v[216:219], v131 offset:20032
	s_waitcnt lgkmcnt(5)
	v_mfma_f32_32x32x16_bf16 v[50:65], v[122:125], v[110:113], v[50:65]
	ds_read_b128 v[122:125], v131 offset:96
	s_waitcnt lgkmcnt(5)
	v_mfma_f32_32x32x16_bf16 v[34:49], v[126:129], v[110:113], v[34:49]
	ds_read_b128 v[126:129], v131 offset:6752
	s_waitcnt lgkmcnt(5)
	v_mfma_f32_32x32x16_bf16 v[82:97], v[184:187], v[98:101], v[82:97]
	ds_read_b128 v[184:187], v131 offset:13408
	s_waitcnt lgkmcnt(5)
	v_mfma_f32_32x32x16_bf16 v[66:81], v[208:211], v[98:101], v[66:81]
	ds_read_b128 v[208:211], v131 offset:20064
	s_waitcnt lgkmcnt(5)
	v_mfma_f32_32x32x16_bf16 v[50:65], v[212:215], v[98:101], v[50:65]
	ds_read_b128 v[212:215], v131 offset:128
	s_waitcnt lgkmcnt(5)
	v_mfma_f32_32x32x16_bf16 v[34:49], v[216:219], v[98:101], v[34:49]
	ds_read_b128 v[216:219], v131 offset:6784
	s_waitcnt lgkmcnt(5)
	v_mfma_f32_32x32x16_bf16 v[82:97], v[122:125], v[106:109], v[82:97]
	ds_read_b128 v[122:125], v131 offset:13440
	s_waitcnt lgkmcnt(5)
	v_mfma_f32_32x32x16_bf16 v[66:81], v[126:129], v[106:109], v[66:81]
	ds_read_b128 v[126:129], v131 offset:20096
	s_waitcnt lgkmcnt(5)
	v_mfma_f32_32x32x16_bf16 v[50:65], v[184:187], v[106:109], v[50:65]
	ds_read_b128 v[184:187], v131 offset:160
	s_waitcnt lgkmcnt(5)
	v_mfma_f32_32x32x16_bf16 v[34:49], v[208:211], v[106:109], v[34:49]
	ds_read_b128 v[208:211], v131 offset:6816
	s_waitcnt lgkmcnt(5)
	v_mfma_f32_32x32x16_bf16 v[82:97], v[212:215], v[118:121], v[82:97]
	ds_read_b128 v[212:215], v131 offset:13472
	s_waitcnt lgkmcnt(5)
	v_mfma_f32_32x32x16_bf16 v[66:81], v[216:219], v[118:121], v[66:81]
	ds_read_b128 v[216:219], v131 offset:20128
	s_waitcnt lgkmcnt(5)
	v_mfma_f32_32x32x16_bf16 v[50:65], v[122:125], v[118:121], v[50:65]
	s_waitcnt lgkmcnt(4)
	v_mfma_f32_32x32x16_bf16 v[34:49], v[126:129], v[118:121], v[34:49]
	s_waitcnt lgkmcnt(3)
	v_mfma_f32_32x32x16_bf16 v[82:97], v[184:187], v[114:117], v[82:97]
	s_waitcnt lgkmcnt(2)
	v_mfma_f32_32x32x16_bf16 v[66:81], v[208:211], v[114:117], v[66:81]
	s_waitcnt lgkmcnt(1)
	v_mfma_f32_32x32x16_bf16 v[50:65], v[212:215], v[114:117], v[50:65]
	s_waitcnt lgkmcnt(0)
	v_mfma_f32_32x32x16_bf16 v[34:49], v[216:219], v[114:117], v[34:49]
	s_nop 8
	v_max3_f32 v131, v82, s45, v83
	v_max3_f32 v131, v131, v84, v85
	v_max3_f32 v131, v131, v86, v87
	v_max3_f32 v239, v50, s45, v51
	v_max3_f32 v131, v131, v88, v89
	v_max3_f32 v239, v239, v52, v53
	v_max3_f32 v131, v131, v90, v91
	v_max3_f32 v239, v239, v54, v55
	v_max3_f32 v131, v131, v92, v93
	v_max3_f32 v239, v239, v56, v57
	v_max3_f32 v131, v131, v94, v95
	v_max3_f32 v239, v239, v58, v59
	v_max3_f32 v131, v131, v96, v97
	v_max3_f32 v239, v239, v60, v61
	v_max3_f32 v131, v131, v66, v67
	v_max3_f32 v239, v239, v62, v63
	v_max3_f32 v131, v131, v68, v69
	v_max3_f32 v239, v239, v64, v65
	v_max3_f32 v131, v131, v70, v71
	v_max3_f32 v239, v239, v34, v35
	v_max3_f32 v131, v131, v72, v73
	v_max3_f32 v239, v239, v36, v37
	v_max3_f32 v131, v131, v74, v75
	v_max3_f32 v239, v239, v38, v39
	v_max3_f32 v131, v131, v76, v77
	v_max3_f32 v239, v239, v40, v41
	v_max3_f32 v131, v131, v78, v79
	v_max3_f32 v239, v239, v42, v43
	v_max3_f32 v131, v131, v80, v81
	v_max3_f32 v239, v239, v44, v45
	v_max3_f32 v239, v239, v46, v47
	v_max3_f32 v239, v239, v48, v49
	v_max_f32_e32 v131, v131, v239
	ds_bpermute_b32 v155, v190, v131
	s_waitcnt lgkmcnt(0)
	v_max3_f32 v131, v133, v131, v155
	v_cmp_gt_f32_e32 vcc, v131, v133
	s_cbranch_vccz .LBB0_824
	v_sub_f32_e32 v133, v133, v131
	v_exp_f32_e32 v184, v133
	s_nop 0
	v_pk_mul_f32 v[32:33], v[32:33], v[184:185] op_sel_hi:[1,0]
	v_pk_mul_f32 v[30:31], v[30:31], v[184:185] op_sel_hi:[1,0]
	v_pk_mul_f32 v[28:29], v[28:29], v[184:185] op_sel_hi:[1,0]
	v_pk_mul_f32 v[26:27], v[26:27], v[184:185] op_sel_hi:[1,0]
	v_pk_mul_f32 v[24:25], v[24:25], v[184:185] op_sel_hi:[1,0]
	v_pk_mul_f32 v[22:23], v[22:23], v[184:185] op_sel_hi:[1,0]
	v_pk_mul_f32 v[20:21], v[20:21], v[184:185] op_sel_hi:[1,0]
	v_pk_mul_f32 v[18:19], v[18:19], v[184:185] op_sel_hi:[1,0]
	v_pk_mul_f32 v[16:17], v[16:17], v[184:185] op_sel_hi:[1,0]
	v_pk_mul_f32 v[14:15], v[14:15], v[184:185] op_sel_hi:[1,0]
	v_pk_mul_f32 v[12:13], v[12:13], v[184:185] op_sel_hi:[1,0]
	v_pk_mul_f32 v[10:11], v[10:11], v[184:185] op_sel_hi:[1,0]
	v_pk_mul_f32 v[8:9], v[8:9], v[184:185] op_sel_hi:[1,0]
	v_pk_mul_f32 v[6:7], v[6:7], v[184:185] op_sel_hi:[1,0]
	v_pk_mul_f32 v[4:5], v[4:5], v[184:185] op_sel_hi:[1,0]
	v_pk_mul_f32 v[2:3], v[2:3], v[184:185] op_sel_hi:[1,0]
	v_mul_f32_e32 v1, v1, v184
.LBB0_824:
	s_barrier
	s_setprio 1
	v_sub_f32_e32 v82, v82, v131
	v_exp_f32_e32 v133, v82
	v_sub_f32_e32 v82, v83, v131
	v_exp_f32_e32 v155, v82
	v_sub_f32_e32 v82, v84, v131
	v_exp_f32_e32 v84, v82
	v_sub_f32_e32 v85, v85, v131
	v_exp_f32_e32 v85, v85
	v_sub_f32_e32 v86, v86, v131
	v_add_f32_e32 v173, 0, v133
	v_exp_f32_e32 v86, v86
	v_sub_f32_e32 v87, v87, v131
	v_add_f32_e32 v173, v155, v173
	v_exp_f32_e32 v87, v87
	v_sub_f32_e32 v88, v88, v131
	v_add_f32_e32 v173, v84, v173
	v_exp_f32_e32 v88, v88
	v_sub_f32_e32 v89, v89, v131
	v_add_f32_e32 v173, v85, v173
	v_exp_f32_e32 v89, v89
	v_sub_f32_e32 v90, v90, v131
	v_add_f32_e32 v173, v86, v173
	v_exp_f32_e32 v90, v90
	v_sub_f32_e32 v91, v91, v131
	v_add_f32_e32 v173, v87, v173
	v_exp_f32_e32 v91, v91
	v_sub_f32_e32 v92, v92, v131
	v_add_f32_e32 v173, v88, v173
	v_exp_f32_e32 v92, v92
	v_sub_f32_e32 v93, v93, v131
	v_add_f32_e32 v173, v89, v173
	v_exp_f32_e32 v93, v93
	v_sub_f32_e32 v94, v94, v131
	v_add_f32_e32 v173, v90, v173
	v_exp_f32_e32 v94, v94
	v_sub_f32_e32 v95, v95, v131
	v_add_f32_e32 v173, v91, v173
	v_exp_f32_e32 v95, v95
	v_sub_f32_e32 v96, v96, v131
	v_add_f32_e32 v173, v92, v173
	v_exp_f32_e32 v96, v96
	v_sub_f32_e32 v97, v97, v131
	v_add_f32_e32 v173, v93, v173
	v_exp_f32_e32 v97, v97
	v_sub_f32_e32 v66, v66, v131
	v_add_f32_e32 v173, v94, v173
	v_exp_f32_e32 v208, v66
	v_sub_f32_e32 v66, v67, v131
	v_add_f32_e32 v173, v95, v173
	v_exp_f32_e32 v209, v66
	v_sub_f32_e32 v66, v68, v131
	v_add_f32_e32 v173, v96, v173
	v_exp_f32_e32 v210, v66
	v_sub_f32_e32 v67, v69, v131
	v_add_f32_e32 v66, v97, v173
	v_exp_f32_e32 v173, v67
	v_sub_f32_e32 v67, v70, v131
	v_add_f32_e32 v66, v208, v66
	v_exp_f32_e32 v211, v67
	v_sub_f32_e32 v67, v71, v131
	v_add_f32_e32 v66, v209, v66
	v_exp_f32_e32 v212, v67
	v_sub_f32_e32 v67, v72, v131
	v_add_f32_e32 v66, v210, v66
	v_exp_f32_e32 v213, v67
	v_sub_f32_e32 v67, v73, v131
	v_add_f32_e32 v66, v173, v66
	v_exp_f32_e32 v214, v67
	v_sub_f32_e32 v67, v74, v131
	v_add_f32_e32 v66, v211, v66
	v_exp_f32_e32 v74, v67
	v_sub_f32_e32 v67, v75, v131
	v_add_f32_e32 v66, v212, v66
	v_exp_f32_e32 v75, v67
	v_sub_f32_e32 v67, v76, v131
	v_add_f32_e32 v66, v213, v66
	v_exp_f32_e32 v76, v67
	v_sub_f32_e32 v67, v77, v131
	v_add_f32_e32 v66, v214, v66
	v_exp_f32_e32 v77, v67
	v_sub_f32_e32 v67, v78, v131
	v_add_f32_e32 v66, v74, v66
	v_exp_f32_e32 v78, v67
	v_sub_f32_e32 v67, v79, v131
	v_add_f32_e32 v66, v75, v66
	v_exp_f32_e32 v79, v67
	v_sub_f32_e32 v67, v80, v131
	v_add_f32_e32 v66, v76, v66
	v_exp_f32_e32 v80, v67
	v_sub_f32_e32 v67, v81, v131
	v_add_f32_e32 v66, v77, v66
	v_exp_f32_e32 v81, v67
	v_sub_f32_e32 v50, v50, v131
	v_add_f32_e32 v66, v78, v66
	v_exp_f32_e32 v215, v50
	v_sub_f32_e32 v50, v51, v131
	v_add_f32_e32 v66, v79, v66
	v_exp_f32_e32 v216, v50
	v_sub_f32_e32 v50, v52, v131
	v_add_f32_e32 v66, v80, v66
	v_exp_f32_e32 v217, v50
	v_add_f32_e32 v50, v81, v66
	v_add_f32_e32 v50, v215, v50
	v_add_f32_e32 v50, v216, v50
	v_add_f32_e32 v218, v217, v50
	v_sub_f32_e32 v50, v53, v131
	v_exp_f32_e32 v219, v50
	v_sub_f32_e32 v50, v54, v131
	v_add3_u32 v54, s12, v189, v205
	v_exp_f32_e32 v220, v50
	v_sub_f32_e32 v50, v55, v131
	v_add_u32_e32 v222, 0x6800, v54
	v_exp_f32_e32 v221, v50
	ds_read_b128 v[50:53], v222
	v_sub_f32_e32 v55, v56, v131
	v_exp_f32_e32 v223, v55
	v_cvt_pk_bf16_f32 v66, v133, v155
	v_cvt_pk_bf16_f32 v67, v84, v85
	v_cvt_pk_bf16_f32 v68, v86, v87
	v_cvt_pk_bf16_f32 v69, v88, v89
	v_add_u32_e32 v84, 0x8900, v54
	ds_read_b128 v[70:73], v84 offset:256
	s_waitcnt lgkmcnt(1)
	v_mfma_f32_32x32x16_bf16 v[18:33], v[50:53], v[66:69], v[18:33]
	v_add_f32_e32 v50, v219, v218
	v_add_f32_e32 v50, v220, v50
	v_add_f32_e32 v50, v221, v50
	v_add_f32_e32 v85, v223, v50
	v_sub_f32_e32 v50, v57, v131
	v_exp_f32_e32 v86, v50
	ds_read_b128 v[50:53], v222 offset:32
	v_sub_f32_e32 v54, v58, v131
	s_waitcnt lgkmcnt(1)
	v_mfma_f32_32x32x16_bf16 v[2:17], v[70:73], v[66:69], v[2:17]
	v_exp_f32_e32 v70, v54
	v_cvt_pk_bf16_f32 v54, v90, v91
	v_cvt_pk_bf16_f32 v55, v92, v93
	v_cvt_pk_bf16_f32 v56, v94, v95
	v_cvt_pk_bf16_f32 v57, v96, v97
	ds_read_b128 v[66:69], v84 offset:288
	v_sub_f32_e32 v34, v34, v131
	s_waitcnt lgkmcnt(1)
	v_mfma_f32_32x32x16_bf16 v[18:33], v[50:53], v[54:57], v[18:33]
	v_add_f32_e32 v50, v86, v85
	v_add_f32_e32 v71, v70, v50
	v_sub_f32_e32 v50, v59, v131
	v_exp_f32_e32 v72, v50
	v_sub_f32_e32 v50, v60, v131
	v_exp_f32_e32 v73, v50
	ds_read_b128 v[50:53], v222 offset:64
	s_waitcnt lgkmcnt(1)
	v_mfma_f32_32x32x16_bf16 v[2:17], v[66:69], v[54:57], v[2:17]
	v_sub_f32_e32 v54, v61, v131
	v_exp_f32_e32 v85, v54
	v_cvt_pk_bf16_f32 v54, v208, v209
	v_cvt_pk_bf16_f32 v55, v210, v173
	v_cvt_pk_bf16_f32 v56, v211, v212
	v_cvt_pk_bf16_f32 v57, v213, v214
	ds_read_b128 v[58:61], v84 offset:320
	v_lshl_add_u64 v[186:187], s[78:79], 0, v[182:183]
	s_waitcnt lgkmcnt(1)
	v_mfma_f32_32x32x16_bf16 v[18:33], v[50:53], v[54:57], v[18:33]
	v_sub_f32_e32 v50, v62, v131
	v_exp_f32_e32 v87, v50
	v_sub_f32_e32 v50, v63, v131
	v_exp_f32_e32 v88, v50
	v_sub_f32_e32 v50, v64, v131
	v_exp_f32_e32 v89, v50
	ds_read_b128 v[50:53], v222 offset:96
	s_waitcnt lgkmcnt(1)
	v_mfma_f32_32x32x16_bf16 v[2:17], v[58:61], v[54:57], v[2:17]
	v_sub_f32_e32 v54, v65, v131
	v_exp_f32_e32 v90, v54
	v_cvt_pk_bf16_f32 v54, v74, v75
	v_cvt_pk_bf16_f32 v55, v76, v77
	v_cvt_pk_bf16_f32 v56, v78, v79
	v_cvt_pk_bf16_f32 v57, v80, v81
	ds_read_b128 v[58:61], v84 offset:352
	v_exp_f32_e32 v74, v34
	s_waitcnt lgkmcnt(1)
	v_mfma_f32_32x32x16_bf16 v[18:33], v[50:53], v[54:57], v[18:33]
	ds_read_b128 v[50:53], v222 offset:128
	v_sub_f32_e32 v34, v35, v131
	v_exp_f32_e32 v75, v34
	v_sub_f32_e32 v34, v36, v131
	v_exp_f32_e32 v76, v34
	v_sub_f32_e32 v34, v37, v131
	v_exp_f32_e32 v77, v34
	v_cvt_pk_bf16_f32 v34, v215, v216
	v_cvt_pk_bf16_f32 v35, v217, v219
	v_cvt_pk_bf16_f32 v36, v220, v221
	v_cvt_pk_bf16_f32 v37, v223, v86
	v_lshl_add_u64 v[184:185], s[78:79], 0, v[180:181]
	v_lshl_add_u64 v[82:83], s[78:79], 0, v[178:179]
	s_waitcnt lgkmcnt(0)
	v_mfma_f32_32x32x16_bf16 v[18:33], v[50:53], v[34:37], v[18:33]
	global_load_dwordx4 v[224:227], v[186:187], off
	global_load_dwordx4 v[232:235], v[82:83], off
	v_sub_f32_e32 v38, v38, v131
	v_exp_f32_e32 v78, v38
	v_sub_f32_e32 v38, v39, v131
	v_exp_f32_e32 v79, v38
	v_sub_f32_e32 v38, v40, v131
	v_mfma_f32_32x32x16_bf16 v[2:17], v[58:61], v[54:57], v[2:17]
	global_load_dwordx4 v[228:231], v[184:185], off
	ds_read_b128 v[54:57], v84 offset:384
	ds_read_b128 v[66:69], v222 offset:160
	v_exp_f32_e32 v80, v38
	v_sub_f32_e32 v42, v42, v131
	s_waitcnt lgkmcnt(1)
	v_mfma_f32_32x32x16_bf16 v[2:17], v[54:57], v[34:37], v[2:17]
	v_sub_f32_e32 v34, v41, v131
	ds_read_b128 v[38:41], v84 offset:416
	v_exp_f32_e32 v81, v34
	v_cvt_pk_bf16_f32 v34, v70, v72
	v_cvt_pk_bf16_f32 v35, v73, v85
	v_cvt_pk_bf16_f32 v36, v87, v88
	v_cvt_pk_bf16_f32 v37, v89, v90
	ds_read_b128 v[54:57], v222 offset:192
	s_add_i32 s0, s0, 0
	s_waitcnt lgkmcnt(2)
	v_mfma_f32_32x32x16_bf16 v[18:33], v[66:69], v[34:37], v[18:33]
	v_exp_f32_e32 v66, v42
	v_sub_f32_e32 v42, v43, v131
	v_exp_f32_e32 v67, v42
	v_sub_f32_e32 v42, v44, v131
	v_exp_f32_e32 v68, v42
	v_sub_f32_e32 v42, v46, v131
	v_exp_f32_e32 v46, v42
	s_waitcnt lgkmcnt(1)
	v_mfma_f32_32x32x16_bf16 v[2:17], v[38:41], v[34:37], v[2:17]
	ds_read_b128 v[38:41], v84 offset:448
	v_sub_f32_e32 v42, v47, v131
	v_sub_f32_e32 v34, v45, v131
	v_exp_f32_e32 v47, v42
	v_sub_f32_e32 v42, v48, v131
	v_exp_f32_e32 v69, v34
	v_cvt_pk_bf16_f32 v34, v74, v75
	v_cvt_pk_bf16_f32 v35, v76, v77
	v_cvt_pk_bf16_f32 v36, v78, v79
	v_cvt_pk_bf16_f32 v37, v80, v81
	v_exp_f32_e32 v48, v42
	ds_read_b128 v[42:45], v222 offset:224
	s_waitcnt lgkmcnt(2)
	v_mfma_f32_32x32x16_bf16 v[18:33], v[54:57], v[34:37], v[18:33]
	s_add_i32 s13, s13, 1
	v_lshl_add_u64 v[174:175], v[174:175], 0, s[6:7]
	v_lshl_add_u64 v[176:177], v[176:177], 0, s[6:7]
	v_lshl_add_u64 v[178:179], v[178:179], 0, s[8:9]
	v_lshl_add_u64 v[180:181], v[180:181], 0, s[8:9]
	s_cmp_eq_u32 s34, s13
	v_lshl_add_u64 v[182:183], v[182:183], 0, s[8:9]
	s_waitcnt lgkmcnt(1)
	v_mfma_f32_32x32x16_bf16 v[2:17], v[38:41], v[34:37], v[2:17]
	v_sub_f32_e32 v34, v49, v131
	v_exp_f32_e32 v49, v34
	ds_read_b128 v[38:41], v84 offset:480
	v_cvt_pk_bf16_f32 v34, v66, v67
	v_cvt_pk_bf16_f32 v35, v68, v69
	v_cvt_pk_bf16_f32 v36, v46, v47
	v_cvt_pk_bf16_f32 v37, v48, v49
	s_waitcnt lgkmcnt(1)
	s_nop 0
	v_mfma_f32_32x32x16_bf16 v[18:33], v[42:45], v[34:37], v[18:33]
	v_add_f32_e32 v42, v72, v71
	v_add_f32_e32 v42, v73, v42
	v_add_f32_e32 v42, v85, v42
	v_add_f32_e32 v42, v87, v42
	v_add_f32_e32 v42, v88, v42
	v_add_f32_e32 v42, v89, v42
	v_add_f32_e32 v42, v90, v42
	s_waitcnt lgkmcnt(0)
	v_mfma_f32_32x32x16_bf16 v[2:17], v[38:41], v[34:37], v[2:17]
	v_add_f32_e32 v34, v74, v42
	v_add_f32_e32 v34, v75, v34
	v_add_f32_e32 v34, v76, v34
	v_add_f32_e32 v34, v77, v34
	v_add_f32_e32 v34, v78, v34
	v_add_f32_e32 v34, v79, v34
	v_add_f32_e32 v34, v80, v34
	v_add_f32_e32 v34, v81, v34
	v_add_f32_e32 v34, v66, v34
	v_add_f32_e32 v34, v67, v34
	v_add_f32_e32 v34, v68, v34
	v_add_f32_e32 v34, v69, v34
	v_add_f32_e32 v34, v46, v34
	v_add_f32_e32 v34, v47, v34
	v_add_f32_e32 v34, v48, v34
	v_add_f32_e32 v34, v49, v34
	v_add_f32_e32 v1, v34, v1
	v_add_u32_e32 v34, s0, v200
	v_add3_u32 v35, v34, v202, s44
	v_add3_u32 v34, v34, v203, s44
	s_waitcnt vmcnt(3)
	ds_write2_b64 v35, v[240:241], v[242:243] offset1:2
	ds_write2_b64 v34, v[244:245], v[246:247] offset1:2
	s_waitcnt lgkmcnt(0)
	s_barrier
	s_cbranch_scc1 .LBB0_826
	v_mov_b32_e32 v133, v131
	s_branch .LBB0_822

.Lmf_entry:
	v_mov_b32_e32 v239, 0
	v_lshl_add_u64 v[174:175], s[98:99], 0, v[174:175]
	v_lshl_add_u64 v[176:177], s[98:99], 0, v[176:177]
	v_lshl_add_u64 v[178:179], s[78:79], 0, v[178:179]
	v_lshl_add_u64 v[180:181], s[78:79], 0, v[180:181]
	v_lshl_add_u64 v[182:183], s[78:79], 0, v[182:183]
	s_mov_b32 s12, 0
	s_mov_b32 s0, 0xac00
	v_add3_u32 v131, s12, v132, v204
	v_add3_u32 v173, s12, v189, v205
	v_add3_u32 v236, s0, v191, v192
	v_add3_u32 v237, s0, v194, v195
	v_add3_u32 v238, s0, v197, v198
	v_add_u32_e32 v155, 0x8900, v173
	v_add_u32_e32 v173, 0x6800, v173
	global_load_dwordx4 v[240:243], v[174:175], off offset:256
	global_load_dwordx4 v[244:247], v[176:177], off offset:256
.Lmf_loop:
	s_setprio 0
	ds_read_b128 v[122:125], v131
	ds_read_b128 v[126:129], v131 offset:6656
	ds_read_b128 v[184:187], v131 offset:13312
	ds_read_b128 v[208:211], v131 offset:19968
	ds_read_b128 v[212:215], v131 offset:32
	ds_read_b128 v[216:219], v131 offset:6688
	s_waitcnt lgkmcnt(5)
	v_mfma_f32_32x32x16_bf16 v[82:97], v[122:125], v[102:105], 0
	ds_read_b128 v[122:125], v131 offset:13344
	s_waitcnt lgkmcnt(5)
	v_mfma_f32_32x32x16_bf16 v[66:81], v[126:129], v[102:105], 0
	ds_read_b128 v[126:129], v131 offset:20000
	s_waitcnt lgkmcnt(5)
	v_mfma_f32_32x32x16_bf16 v[50:65], v[184:187], v[102:105], 0
	ds_read_b128 v[184:187], v131 offset:64
	s_waitcnt lgkmcnt(5)
	v_mfma_f32_32x32x16_bf16 v[34:49], v[208:211], v[102:105], 0
	ds_read_b128 v[208:211], v131 offset:6720
	s_waitcnt lgkmcnt(5)
	v_mfma_f32_32x32x16_bf16 v[82:97], v[212:215], v[110:113], v[82:97]
	ds_read_b128 v[212:215], v131 offset:13376
	s_waitcnt lgkmcnt(5)
	v_mfma_f32_32x32x16_bf16 v[66:81], v[216:219], v[110:113], v[66:81]
	s_waitcnt vmcnt(2)
	ds_write_b128 v236, v[224:227]
	ds_write_b128 v237, v[228:231]
	ds_write_b128 v238, v[232:235]
	ds_read_b128 v[216:219], v131 offset:20032
	s_waitcnt lgkmcnt(5)
	v_mfma_f32_32x32x16_bf16 v[50:65], v[122:125], v[110:113], v[50:65]
	ds_read_b128 v[122:125], v131 offset:96
	s_waitcnt lgkmcnt(5)
	v_mfma_f32_32x32x16_bf16 v[34:49], v[126:129], v[110:113], v[34:49]
	ds_read_b128 v[126:129], v131 offset:6752
	s_waitcnt lgkmcnt(5)
	v_mfma_f32_32x32x16_bf16 v[82:97], v[184:187], v[98:101], v[82:97]
	ds_read_b128 v[184:187], v131 offset:13408
	s_waitcnt lgkmcnt(5)
	v_mfma_f32_32x32x16_bf16 v[66:81], v[208:211], v[98:101], v[66:81]
	ds_read_b128 v[208:211], v131 offset:20064
	s_waitcnt lgkmcnt(5)
	v_mfma_f32_32x32x16_bf16 v[50:65], v[212:215], v[98:101], v[50:65]
	ds_read_b128 v[212:215], v131 offset:128
	s_waitcnt lgkmcnt(5)
	v_mfma_f32_32x32x16_bf16 v[34:49], v[216:219], v[98:101], v[34:49]
	ds_read_b128 v[216:219], v131 offset:6784
	s_waitcnt lgkmcnt(5)
	v_mfma_f32_32x32x16_bf16 v[82:97], v[122:125], v[106:109], v[82:97]
	ds_read_b128 v[122:125], v131 offset:13440
	s_waitcnt lgkmcnt(5)
	v_mfma_f32_32x32x16_bf16 v[66:81], v[126:129], v[106:109], v[66:81]
	ds_read_b128 v[126:129], v131 offset:20096
	s_waitcnt lgkmcnt(5)
	v_mfma_f32_32x32x16_bf16 v[50:65], v[184:187], v[106:109], v[50:65]
	ds_read_b128 v[184:187], v131 offset:160
	s_waitcnt lgkmcnt(5)
	v_mfma_f32_32x32x16_bf16 v[34:49], v[208:211], v[106:109], v[34:49]
	ds_read_b128 v[208:211], v131 offset:6816
	s_waitcnt lgkmcnt(5)
	v_mfma_f32_32x32x16_bf16 v[82:97], v[212:215], v[118:121], v[82:97]
	ds_read_b128 v[212:215], v131 offset:13472
	s_waitcnt lgkmcnt(5)
	v_mfma_f32_32x32x16_bf16 v[66:81], v[216:219], v[118:121], v[66:81]
	ds_read_b128 v[216:219], v131 offset:20128
	s_waitcnt lgkmcnt(5)
	v_mfma_f32_32x32x16_bf16 v[50:65], v[122:125], v[118:121], v[50:65]
	s_waitcnt lgkmcnt(4)
	v_mfma_f32_32x32x16_bf16 v[34:49], v[126:129], v[118:121], v[34:49]
	s_waitcnt lgkmcnt(3)
	v_mfma_f32_32x32x16_bf16 v[82:97], v[184:187], v[114:117], v[82:97]
	s_waitcnt lgkmcnt(2)
	v_mfma_f32_32x32x16_bf16 v[66:81], v[208:211], v[114:117], v[66:81]
	s_waitcnt lgkmcnt(1)
	v_mfma_f32_32x32x16_bf16 v[50:65], v[212:215], v[114:117], v[50:65]
	s_waitcnt lgkmcnt(0)
	v_mfma_f32_32x32x16_bf16 v[34:49], v[216:219], v[114:117], v[34:49]
	s_barrier
	s_setprio 1
	ds_read_b128 v[122:125], v173
	ds_read_b128 v[126:129], v155 offset:256
	ds_read_b128 v[184:187], v173 offset:32
	ds_read_b128 v[208:211], v155 offset:288
	ds_read_b128 v[212:215], v173 offset:64
	ds_read_b128 v[216:219], v155 offset:320
	v_exp_f32_e32 v82, v82
	v_exp_f32_e32 v83, v83
	v_exp_f32_e32 v84, v84
	v_exp_f32_e32 v85, v85
	v_exp_f32_e32 v86, v86
	v_exp_f32_e32 v87, v87
	v_exp_f32_e32 v88, v88
	v_exp_f32_e32 v89, v89
	v_add_f32_e32 v1, v82, v1
	v_add_f32_e32 v239, v83, v239
	v_add_f32_e32 v1, v84, v1
	v_add_f32_e32 v239, v85, v239
	v_add_f32_e32 v1, v86, v1
	v_add_f32_e32 v239, v87, v239
	v_add_f32_e32 v1, v88, v1
	v_add_f32_e32 v239, v89, v239
	v_cvt_pk_bf16_f32 v82, v82, v83
	v_cvt_pk_bf16_f32 v83, v84, v85
	v_cvt_pk_bf16_f32 v84, v86, v87
	v_cvt_pk_bf16_f32 v85, v88, v89
	s_waitcnt lgkmcnt(4)
	v_exp_f32_e32 v90, v90
	v_exp_f32_e32 v91, v91
	v_exp_f32_e32 v92, v92
	v_exp_f32_e32 v93, v93
	v_mfma_f32_32x32x16_bf16 v[18:33], v[122:125], v[82:85], v[18:33]
	v_exp_f32_e32 v94, v94
	v_exp_f32_e32 v95, v95
	v_exp_f32_e32 v96, v96
	v_exp_f32_e32 v97, v97
	v_mfma_f32_32x32x16_bf16 v[2:17], v[126:129], v[82:85], v[2:17]
	ds_read_b128 v[122:125], v173 offset:96
	ds_read_b128 v[126:129], v155 offset:352
	v_add_f32_e32 v1, v90, v1
	v_add_f32_e32 v239, v91, v239
	v_add_f32_e32 v1, v92, v1
	v_add_f32_e32 v239, v93, v239
	v_add_f32_e32 v1, v94, v1
	v_add_f32_e32 v239, v95, v239
	v_add_f32_e32 v1, v96, v1
	v_add_f32_e32 v239, v97, v239
	v_cvt_pk_bf16_f32 v90, v90, v91
	v_cvt_pk_bf16_f32 v91, v92, v93
	v_cvt_pk_bf16_f32 v92, v94, v95
	v_cvt_pk_bf16_f32 v93, v96, v97
	s_waitcnt lgkmcnt(4)
	v_exp_f32_e32 v66, v66
	v_exp_f32_e32 v67, v67
	v_exp_f32_e32 v68, v68
	v_exp_f32_e32 v69, v69
	v_mfma_f32_32x32x16_bf16 v[18:33], v[184:187], v[90:93], v[18:33]
	v_exp_f32_e32 v70, v70
	v_exp_f32_e32 v71, v71
	v_exp_f32_e32 v72, v72
	v_exp_f32_e32 v73, v73
	v_mfma_f32_32x32x16_bf16 v[2:17], v[208:211], v[90:93], v[2:17]
	ds_read_b128 v[184:187], v173 offset:128
	ds_read_b128 v[208:211], v155 offset:384
	v_add_f32_e32 v1, v66, v1
	v_add_f32_e32 v239, v67, v239
	v_add_f32_e32 v1, v68, v1
	v_add_f32_e32 v239, v69, v239
	v_add_f32_e32 v1, v70, v1
	v_add_f32_e32 v239, v71, v239
	v_add_f32_e32 v1, v72, v1
	v_add_f32_e32 v239, v73, v239
	v_cvt_pk_bf16_f32 v66, v66, v67
	v_cvt_pk_bf16_f32 v67, v68, v69
	v_cvt_pk_bf16_f32 v68, v70, v71
	v_cvt_pk_bf16_f32 v69, v72, v73
	s_waitcnt lgkmcnt(4)
	v_exp_f32_e32 v74, v74
	v_exp_f32_e32 v75, v75
	v_exp_f32_e32 v76, v76
	v_exp_f32_e32 v77, v77
	v_mfma_f32_32x32x16_bf16 v[18:33], v[212:215], v[66:69], v[18:33]
	v_exp_f32_e32 v78, v78
	v_exp_f32_e32 v79, v79
	v_exp_f32_e32 v80, v80
	v_exp_f32_e32 v81, v81
	v_mfma_f32_32x32x16_bf16 v[2:17], v[216:219], v[66:69], v[2:17]
	ds_read_b128 v[212:215], v173 offset:160
	ds_read_b128 v[216:219], v155 offset:416
	v_add_f32_e32 v1, v74, v1
	v_add_f32_e32 v239, v75, v239
	v_add_f32_e32 v1, v76, v1
	v_add_f32_e32 v239, v77, v239
	v_add_f32_e32 v1, v78, v1
	v_add_f32_e32 v239, v79, v239
	v_add_f32_e32 v1, v80, v1
	v_add_f32_e32 v239, v81, v239
	v_cvt_pk_bf16_f32 v74, v74, v75
	v_cvt_pk_bf16_f32 v75, v76, v77
	v_cvt_pk_bf16_f32 v76, v78, v79
	v_cvt_pk_bf16_f32 v77, v80, v81
	s_waitcnt lgkmcnt(4)
	v_exp_f32_e32 v50, v50
	v_exp_f32_e32 v51, v51
	v_exp_f32_e32 v52, v52
	v_exp_f32_e32 v53, v53
	v_mfma_f32_32x32x16_bf16 v[18:33], v[122:125], v[74:77], v[18:33]
	v_exp_f32_e32 v54, v54
	v_exp_f32_e32 v55, v55
	v_exp_f32_e32 v56, v56
	v_exp_f32_e32 v57, v57
	v_mfma_f32_32x32x16_bf16 v[2:17], v[126:129], v[74:77], v[2:17]
	ds_read_b128 v[122:125], v173 offset:192
	ds_read_b128 v[126:129], v155 offset:448
	global_load_dwordx4 v[224:227], v[182:183], off
	global_load_dwordx4 v[228:231], v[180:181], off
	global_load_dwordx4 v[232:235], v[178:179], off
	v_add_f32_e32 v1, v50, v1
	v_add_f32_e32 v239, v51, v239
	v_add_f32_e32 v1, v52, v1
	v_add_f32_e32 v239, v53, v239
	v_add_f32_e32 v1, v54, v1
	v_add_f32_e32 v239, v55, v239
	v_add_f32_e32 v1, v56, v1
	v_add_f32_e32 v239, v57, v239
	v_cvt_pk_bf16_f32 v50, v50, v51
	v_cvt_pk_bf16_f32 v51, v52, v53
	v_cvt_pk_bf16_f32 v52, v54, v55
	v_cvt_pk_bf16_f32 v53, v56, v57
	s_waitcnt lgkmcnt(4)
	v_exp_f32_e32 v58, v58
	v_exp_f32_e32 v59, v59
	v_exp_f32_e32 v60, v60
	v_exp_f32_e32 v61, v61
	v_mfma_f32_32x32x16_bf16 v[18:33], v[184:187], v[50:53], v[18:33]
	v_exp_f32_e32 v62, v62
	v_exp_f32_e32 v63, v63
	v_exp_f32_e32 v64, v64
	v_exp_f32_e32 v65, v65
	v_mfma_f32_32x32x16_bf16 v[2:17], v[208:211], v[50:53], v[2:17]
	ds_read_b128 v[184:187], v173 offset:224
	ds_read_b128 v[208:211], v155 offset:480
	v_add_f32_e32 v1, v58, v1
	v_add_f32_e32 v239, v59, v239
	v_add_f32_e32 v1, v60, v1
	v_add_f32_e32 v239, v61, v239
	v_add_f32_e32 v1, v62, v1
	v_add_f32_e32 v239, v63, v239
	v_add_f32_e32 v1, v64, v1
	v_add_f32_e32 v239, v65, v239
	v_cvt_pk_bf16_f32 v58, v58, v59
	v_cvt_pk_bf16_f32 v59, v60, v61
	v_cvt_pk_bf16_f32 v60, v62, v63
	v_cvt_pk_bf16_f32 v61, v64, v65
	s_waitcnt lgkmcnt(4)
	v_exp_f32_e32 v34, v34
	v_exp_f32_e32 v35, v35
	v_exp_f32_e32 v36, v36
	v_exp_f32_e32 v37, v37
	v_mfma_f32_32x32x16_bf16 v[18:33], v[212:215], v[58:61], v[18:33]
	v_exp_f32_e32 v38, v38
	v_exp_f32_e32 v39, v39
	v_exp_f32_e32 v40, v40
	v_exp_f32_e32 v41, v41
	v_mfma_f32_32x32x16_bf16 v[2:17], v[216:219], v[58:61], v[2:17]
	v_lshl_add_u64 v[174:175], v[174:175], 0, s[6:7]
	v_lshl_add_u64 v[176:177], v[176:177], 0, s[6:7]
	v_lshl_add_u64 v[178:179], v[178:179], 0, s[8:9]
	v_lshl_add_u64 v[180:181], v[180:181], 0, s[8:9]
	v_lshl_add_u64 v[182:183], v[182:183], 0, s[8:9]
	v_add_f32_e32 v1, v34, v1
	v_add_f32_e32 v239, v35, v239
	v_add_f32_e32 v1, v36, v1
	v_add_f32_e32 v239, v37, v239
	v_add_f32_e32 v1, v38, v1
	v_add_f32_e32 v239, v39, v239
	v_add_f32_e32 v1, v40, v1
	v_add_f32_e32 v239, v41, v239
	v_cvt_pk_bf16_f32 v34, v34, v35
	v_cvt_pk_bf16_f32 v35, v36, v37
	v_cvt_pk_bf16_f32 v36, v38, v39
	v_cvt_pk_bf16_f32 v37, v40, v41
	s_waitcnt lgkmcnt(2)
	v_exp_f32_e32 v42, v42
	v_exp_f32_e32 v43, v43
	v_exp_f32_e32 v44, v44
	v_exp_f32_e32 v45, v45
	v_mfma_f32_32x32x16_bf16 v[18:33], v[122:125], v[34:37], v[18:33]
	v_exp_f32_e32 v46, v46
	v_exp_f32_e32 v47, v47
	v_exp_f32_e32 v48, v48
	v_exp_f32_e32 v49, v49
	v_mfma_f32_32x32x16_bf16 v[2:17], v[126:129], v[34:37], v[2:17]
	v_add_f32_e32 v1, v42, v1
	v_add_f32_e32 v239, v43, v239
	v_add_f32_e32 v1, v44, v1
	v_add_f32_e32 v239, v45, v239
	v_add_f32_e32 v1, v46, v1
	v_add_f32_e32 v239, v47, v239
	v_add_f32_e32 v1, v48, v1
	v_add_f32_e32 v239, v49, v239
	v_cvt_pk_bf16_f32 v42, v42, v43
	v_cvt_pk_bf16_f32 v43, v44, v45
	v_cvt_pk_bf16_f32 v44, v46, v47
	v_cvt_pk_bf16_f32 v45, v48, v49
	s_waitcnt lgkmcnt(0)
	s_nop 0
	v_mfma_f32_32x32x16_bf16 v[18:33], v[184:187], v[42:45], v[18:33]
	v_mfma_f32_32x32x16_bf16 v[2:17], v[208:211], v[42:45], v[2:17]
	s_add_i32 s13, s13, 1
	v_add_u32_e32 v220, s0, v200
	v_add3_u32 v221, v220, v202, s44
	v_add3_u32 v220, v220, v203, s44
	s_waitcnt vmcnt(3)
	ds_write2_b64 v221, v[240:241], v[242:243] offset1:2
	ds_write2_b64 v220, v[244:245], v[246:247] offset1:2
	v_add3_u32 v131, s0, v132, v204
	v_add3_u32 v173, s0, v189, v205
	v_add3_u32 v236, s12, v191, v192
	v_add3_u32 v237, s12, v194, v195
	v_add3_u32 v238, s12, v197, v198
	v_add_u32_e32 v155, 0x8900, v173
	v_add_u32_e32 v173, 0x6800, v173
	s_cmp_eq_u32 s34, s13
	s_waitcnt lgkmcnt(0)
	global_load_dwordx4 v[240:243], v[174:175], off offset:256
	global_load_dwordx4 v[244:247], v[176:177], off offset:256
	s_barrier
	s_cbranch_scc1 .Lmf_final
	s_xor_b32 s0, s0, 0xac00
	s_xor_b32 s12, s12, 0xac00
	s_branch .Lmf_loop
.Lmf_final:
	s_setprio 0
	v_add_f32_e32 v1, v1, v239
	v_add3_u32 v133, s0, v132, v204
	ds_read_b128 v[34:37], v133
	ds_read_b128 v[122:125], v133 offset:32
	s_waitcnt lgkmcnt(1)
	v_mfma_f32_32x32x16_bf16 v[82:97], v[34:37], v[102:105], 0
	ds_read_b128 v[34:37], v133 offset:6656
	ds_read_b128 v[126:129], v133 offset:6688
	s_waitcnt lgkmcnt(1)
	v_mfma_f32_32x32x16_bf16 v[66:81], v[34:37], v[102:105], 0
	ds_read_b128 v[34:37], v133 offset:13312
	ds_read_b128 v[174:177], v133 offset:13344
	s_waitcnt lgkmcnt(1)
	v_mfma_f32_32x32x16_bf16 v[50:65], v[34:37], v[102:105], 0
	ds_read_b128 v[34:37], v133 offset:19968
	ds_read_b128 v[178:181], v133 offset:20000
	s_waitcnt lgkmcnt(1)
	v_mfma_f32_32x32x16_bf16 v[34:49], v[34:37], v[102:105], 0
	v_mfma_f32_32x32x16_bf16 v[82:97], v[122:125], v[110:113], v[82:97]
	v_mfma_f32_32x32x16_bf16 v[66:81], v[126:129], v[110:113], v[66:81]
	v_mfma_f32_32x32x16_bf16 v[50:65], v[174:177], v[110:113], v[50:65]
	s_waitcnt lgkmcnt(0)
	v_mfma_f32_32x32x16_bf16 v[34:49], v[178:181], v[110:113], v[34:49]
	ds_read_b128 v[102:105], v133 offset:64
	ds_read_b128 v[110:113], v133 offset:96
	s_waitcnt lgkmcnt(1)
	v_mfma_f32_32x32x16_bf16 v[82:97], v[102:105], v[98:101], v[82:97]
	ds_read_b128 v[102:105], v133 offset:6720
	ds_read_b128 v[122:125], v133 offset:6752
	s_waitcnt lgkmcnt(1)
	v_mfma_f32_32x32x16_bf16 v[66:81], v[102:105], v[98:101], v[66:81]
	ds_read_b128 v[102:105], v133 offset:13376
	ds_read_b128 v[126:129], v133 offset:13408
	s_waitcnt lgkmcnt(1)
	v_mfma_f32_32x32x16_bf16 v[50:65], v[102:105], v[98:101], v[50:65]
	ds_read_b128 v[102:105], v133 offset:20032
	ds_read_b128 v[174:177], v133 offset:20064
	v_mfma_f32_32x32x16_bf16 v[82:97], v[110:113], v[106:109], v[82:97]
	s_waitcnt lgkmcnt(1)
	v_mfma_f32_32x32x16_bf16 v[34:49], v[102:105], v[98:101], v[34:49]
	ds_read_b128 v[98:101], v133 offset:128
	ds_read_b128 v[102:105], v133 offset:160
	v_mfma_f32_32x32x16_bf16 v[66:81], v[122:125], v[106:109], v[66:81]
	s_waitcnt lgkmcnt(1)
	v_mfma_f32_32x32x16_bf16 v[82:97], v[98:101], v[118:121], v[82:97]
	v_mfma_f32_32x32x16_bf16 v[50:65], v[126:129], v[106:109], v[50:65]
	v_mfma_f32_32x32x16_bf16 v[34:49], v[174:177], v[106:109], v[34:49]
	ds_read_b128 v[98:101], v133 offset:6784
	ds_read_b128 v[106:109], v133 offset:6816
	s_waitcnt lgkmcnt(1)
	v_mfma_f32_32x32x16_bf16 v[66:81], v[98:101], v[118:121], v[66:81]
	ds_read_b128 v[98:101], v133 offset:13440
	ds_read_b128 v[110:113], v133 offset:13472
	v_mfma_f32_32x32x16_bf16 v[82:97], v[102:105], v[114:117], v[82:97]
	s_waitcnt lgkmcnt(1)
	v_mfma_f32_32x32x16_bf16 v[50:65], v[98:101], v[118:121], v[50:65]
	s_nop 9
	ds_read_b128 v[98:101], v133 offset:20096
	ds_read_b128 v[102:105], v133 offset:20128
	v_mfma_f32_32x32x16_bf16 v[66:81], v[106:109], v[114:117], v[66:81]
	s_nop 6
	s_waitcnt lgkmcnt(2)
	v_mfma_f32_32x32x16_bf16 v[50:65], v[110:113], v[114:117], v[50:65]
	s_waitcnt lgkmcnt(1)
	v_mfma_f32_32x32x16_bf16 v[34:49], v[98:101], v[118:121], v[34:49]
	s_nop 2
	s_waitcnt lgkmcnt(0)
	v_mfma_f32_32x32x16_bf16 v[34:49], v[102:105], v[114:117], v[34:49]
	s_nop 10
	s_barrier
	s_setprio 1
	v_exp_f32_e32 v99, v66
	v_exp_f32_e32 v100, v67
	v_exp_f32_e32 v101, v68
	v_exp_f32_e32 v102, v69
	v_exp_f32_e32 v103, v70
	v_exp_f32_e32 v104, v71
	v_exp_f32_e32 v105, v72
	v_exp_f32_e32 v106, v73
	v_exp_f32_e32 v74, v74
	v_exp_f32_e32 v75, v75
	v_exp_f32_e32 v76, v76
	v_exp_f32_e32 v77, v77
	v_exp_f32_e32 v78, v78
	v_exp_f32_e32 v79, v79
	v_add3_u32 v70, s0, v189, v205
	v_exp_f32_e32 v80, v80
	v_add_u32_e32 v109, 0x6800, v70
	v_exp_f32_e32 v81, v81
	ds_read_b128 v[66:69], v109
	v_add_u32_e32 v112, 0x8900, v70
	v_exp_f32_e32 v82, v82
	v_exp_f32_e32 v83, v83
	v_exp_f32_e32 v84, v84
	v_exp_f32_e32 v85, v85
	v_exp_f32_e32 v86, v86
	v_exp_f32_e32 v87, v87
	v_exp_f32_e32 v88, v88
	v_exp_f32_e32 v89, v89
	ds_read_b128 v[70:73], v112 offset:256
	v_exp_f32_e32 v107, v50
	v_exp_f32_e32 v108, v51
	v_exp_f32_e32 v110, v52
	v_mov_b32_e32 v111, v53
	v_cvt_pk_bf16_f32 v50, v82, v83
	v_cvt_pk_bf16_f32 v51, v84, v85
	v_cvt_pk_bf16_f32 v52, v86, v87
	v_cvt_pk_bf16_f32 v53, v88, v89
	v_exp_f32_e32 v113, v54
	s_waitcnt lgkmcnt(1)
	v_mfma_f32_32x32x16_bf16 v[18:33], v[66:69], v[50:53], v[18:33]
	ds_read_b128 v[66:69], v109 offset:32
	v_exp_f32_e32 v114, v55
	v_exp_f32_e32 v90, v90
	v_exp_f32_e32 v91, v91
	v_exp_f32_e32 v92, v92
	v_exp_f32_e32 v93, v93
	v_exp_f32_e32 v94, v94
	v_exp_f32_e32 v95, v95
	v_exp_f32_e32 v96, v96
	v_exp_f32_e32 v97, v97
	s_waitcnt lgkmcnt(1)
	v_mfma_f32_32x32x16_bf16 v[2:17], v[70:73], v[50:53], v[2:17]
	v_exp_f32_e32 v70, v56
	v_mov_b32_e32 v71, v57
	ds_read_b128 v[54:57], v112 offset:288
	v_cvt_pk_bf16_f32 v50, v90, v91
	v_cvt_pk_bf16_f32 v51, v92, v93
	v_cvt_pk_bf16_f32 v52, v94, v95
	v_cvt_pk_bf16_f32 v53, v96, v97
	v_exp_f32_e32 v72, v58
	s_waitcnt lgkmcnt(1)
	v_mfma_f32_32x32x16_bf16 v[18:33], v[66:69], v[50:53], v[18:33]
	ds_read_b128 v[66:69], v109 offset:64
	v_exp_f32_e32 v73, v59
	v_exp_f32_e32 v115, v60
	v_exp_f32_e32 v111, v111
	s_waitcnt lgkmcnt(1)
	v_mfma_f32_32x32x16_bf16 v[2:17], v[54:57], v[50:53], v[2:17]
	ds_read_b128 v[54:57], v112 offset:320
	v_cvt_pk_bf16_f32 v50, v99, v100
	v_cvt_pk_bf16_f32 v51, v101, v102
	v_cvt_pk_bf16_f32 v52, v103, v104
	v_cvt_pk_bf16_f32 v53, v105, v106
	v_exp_f32_e32 v71, v71
	s_waitcnt lgkmcnt(1)
	v_mfma_f32_32x32x16_bf16 v[18:33], v[66:69], v[50:53], v[18:33]
	v_exp_f32_e32 v66, v61
	v_exp_f32_e32 v62, v62
	v_exp_f32_e32 v63, v63
	ds_read_b128 v[58:61], v109 offset:96
	v_exp_f32_e32 v67, v34
	s_waitcnt lgkmcnt(1)
	v_mfma_f32_32x32x16_bf16 v[2:17], v[54:57], v[50:53], v[2:17]
	ds_read_b128 v[54:57], v112 offset:352
	v_cvt_pk_bf16_f32 v50, v74, v75
	v_cvt_pk_bf16_f32 v51, v76, v77
	v_cvt_pk_bf16_f32 v52, v78, v79
	v_cvt_pk_bf16_f32 v53, v80, v81
	v_exp_f32_e32 v68, v35
	s_waitcnt lgkmcnt(1)
	v_mfma_f32_32x32x16_bf16 v[18:33], v[58:61], v[50:53], v[18:33]
	ds_read_b128 v[58:61], v109 offset:128
	v_exp_f32_e32 v69, v36
	v_cvt_pk_bf16_f32 v34, v107, v108
	v_cvt_pk_bf16_f32 v35, v110, v111
	v_cvt_pk_bf16_f32 v36, v113, v114
	s_waitcnt lgkmcnt(1)
	v_mfma_f32_32x32x16_bf16 v[2:17], v[54:57], v[50:53], v[2:17]
	ds_read_b128 v[50:53], v112 offset:384
	v_mov_b32_e32 v54, v37
	v_cvt_pk_bf16_f32 v37, v70, v71
	v_exp_f32_e32 v64, v64
	v_exp_f32_e32 v65, v65
	s_waitcnt lgkmcnt(1)
	v_mfma_f32_32x32x16_bf16 v[18:33], v[58:61], v[34:37], v[18:33]
	v_exp_f32_e32 v58, v54
	v_exp_f32_e32 v59, v38
	ds_read_b128 v[54:57], v109 offset:160
	v_exp_f32_e32 v60, v39
	v_exp_f32_e32 v61, v40
	s_waitcnt lgkmcnt(1)
	v_mfma_f32_32x32x16_bf16 v[2:17], v[50:53], v[34:37], v[2:17]
	v_mov_b32_e32 v50, v41
	ds_read_b128 v[38:41], v112 offset:416
	v_cvt_pk_bf16_f32 v34, v72, v73
	v_cvt_pk_bf16_f32 v35, v115, v66
	v_cvt_pk_bf16_f32 v36, v62, v63
	v_cvt_pk_bf16_f32 v37, v64, v65
	s_waitcnt lgkmcnt(1)
	s_nop 0
	v_mfma_f32_32x32x16_bf16 v[18:33], v[54:57], v[34:37], v[18:33]
	v_exp_f32_e32 v54, v50
	ds_read_b128 v[50:53], v109 offset:192
	v_exp_f32_e32 v55, v42
	v_exp_f32_e32 v56, v43
	v_exp_f32_e32 v57, v44
	s_waitcnt lgkmcnt(1)
	v_mfma_f32_32x32x16_bf16 v[2:17], v[38:41], v[34:37], v[2:17]
	ds_read_b128 v[38:41], v112 offset:448
	v_cvt_pk_bf16_f32 v34, v67, v68
	v_cvt_pk_bf16_f32 v35, v69, v58
	v_cvt_pk_bf16_f32 v36, v59, v60
	v_cvt_pk_bf16_f32 v37, v61, v54
	v_exp_f32_e32 v48, v48
	s_lshl_b64 s[10:11], s[10:11], 10
	s_waitcnt lgkmcnt(1)
	v_mfma_f32_32x32x16_bf16 v[18:33], v[50:53], v[34:37], v[18:33]
	v_exp_f32_e32 v50, v45
	v_exp_f32_e32 v46, v46
	v_exp_f32_e32 v47, v47
	ds_read_b128 v[42:45], v109 offset:224
	s_add_u32 s0, s36, s10
	s_waitcnt lgkmcnt(1)
	v_mfma_f32_32x32x16_bf16 v[2:17], v[38:41], v[34:37], v[2:17]
	ds_read_b128 v[38:41], v112 offset:480
	v_exp_f32_e32 v49, v49
	v_cvt_pk_bf16_f32 v34, v55, v56
	v_cvt_pk_bf16_f32 v35, v57, v50
	v_cvt_pk_bf16_f32 v36, v46, v47
	v_cvt_pk_bf16_f32 v37, v48, v49
	s_addc_u32 s11, s37, s11
	s_lshl_b32 s10, s49, 7
	s_waitcnt lgkmcnt(1)
	v_mfma_f32_32x32x16_bf16 v[18:33], v[42:45], v[34:37], v[18:33]
	s_add_u32 s10, s0, s10
	s_addc_u32 s11, s11, 0
	s_waitcnt lgkmcnt(0)
	s_cmpk_lt_i32 s40, 0x100
	s_cbranch_scc0 .Lmf_fin_nobar
	s_barrier
